# sample attention: dilation-1 rows loaded with default cache policy (re-read by other tokens and dilations), dilation-4/16 rows streamed nt
# speedup vs baseline: 1.0089x; 1.0089x over previous
; __device__ __forceinline__ float fexp2(float x) { return __builtin_amdgcn_exp2f(x); }
; __device__ __forceinline__ void attn_sample_item(const P& p, int wi, int lane) {
;     ...
;         for (int jj = 0; jj < 33; ++jj) {
;             const int j = 4 * jj + kg; const bool valid = j <= 128; const int jc = valid ? j : 128;
;             const int idx = 2048 + i - d * jc;
;             f32x4 k0, k1, v0, v1;
;             if (idx < 2048) { const size_t off = (((size_t)bs * 2048 + idx) * 8 + h) * 128 + 8 * li;
;                 k0 = __builtin_nontemporal_load((const f32x4*)(p.cache_k + off)); k1 = __builtin_nontemporal_load((const f32x4*)(p.cache_k + off + 4)); v0 = __builtin_nontemporal_load((const f32x4*)(p.cache_v + off)); v1 = __builtin_nontemporal_load((const f32x4*)(p.cache_v + off + 4)); }
;             else { const int nr = bs * 4 + (idx - 2048); const float rsn = rstd1[TP + nr]; const int c0 = 4096 + h * 128 + 8 * li;
;                 k0 = acc1_4(ACC1, nr, c0) * rsn; k1 = acc1_4(ACC1, nr, c0 + 4) * rsn; v0 = acc1_4(ACC1, nr, c0 + 1024) * rsn; v1 = acc1_4(ACC1, nr, c0 + 1028) * rsn; }
;             float dot = (q[0] * k0[0] + q[1] * k0[1]) + (q[2] * k0[2] + q[3] * k0[3]) + (q[4] * k1[0] + q[5] * k1[1]) + (q[6] * k1[2] + q[7] * k1[3]);
;             dot += __shfl_xor(dot, 1); dot += __shfl_xor(dot, 2); dot += __shfl_xor(dot, 4); dot += __shfl_xor(dot, 8);
;             const float s = valid ? dot - sl * (float)(d * j) : -INFINITY;
;             const float mn = fmaxf(m, s), sc = fexp2(m - mn), pe = fexp2(s - mn);
;             l = l * sc + pe;
;             acc[0] = acc[0] * sc + pe * v0[0]; acc[1] = acc[1] * sc + pe * v0[1]; acc[2] = acc[2] * sc + pe * v0[2]; acc[3] = acc[3] * sc + pe * v0[3];
;             acc[4] = acc[4] * sc + pe * v1[0]; acc[5] = acc[5] * sc + pe * v1[1]; acc[6] = acc[6] * sc + pe * v1[2]; acc[7] = acc[7] * sc + pe * v1[3];
;             m = mn;
;         }
.Las_slot1:
	s_waitcnt vmcnt(28)
	v_fma_f32 v197, v160, v16, v194
	v_fmac_f32_e32 v197, v161, v17
	v_fmac_f32_e32 v197, v162, v18
	v_fmac_f32_e32 v197, v163, v19
	v_fmac_f32_e32 v197, v164, v20
	v_fmac_f32_e32 v197, v165, v21
	v_fmac_f32_e32 v197, v166, v22
	v_fmac_f32_e32 v197, v167, v23
	s_nop 1
	v_add_f32_dpp v197, v197, v197 row_ror:8 row_mask:0xf bank_mask:0xf
	s_nop 1
	v_add_f32_dpp v197, v197, v197 row_ror:4 row_mask:0xf bank_mask:0xf
	s_nop 1
	v_add_f32_dpp v197, v197, v197 row_ror:2 row_mask:0xf bank_mask:0xf
	s_nop 1
	v_add_f32_dpp v197, v197, v197 row_ror:1 row_mask:0xf bank_mask:0xf
	v_max_f32_e32 v198, v192, v197
	v_sub_f32_e32 v199, v192, v198
	v_sub_f32_e32 v200, v197, v198
	v_exp_f32_e32 v199, v199
	v_exp_f32_e32 v200, v200
	v_mov_b32_e32 v192, v198
	v_fma_f32 v193, v193, v199, v200
	v_mul_f32_e32 v168, v168, v199
	v_mul_f32_e32 v169, v169, v199
	v_mul_f32_e32 v170, v170, v199
	v_mul_f32_e32 v171, v171, v199
	v_mul_f32_e32 v172, v172, v199
	v_mul_f32_e32 v173, v173, v199
	v_mul_f32_e32 v174, v174, v199
	v_mul_f32_e32 v175, v175, v199
	v_fmac_f32_e32 v168, v200, v24
	v_fmac_f32_e32 v169, v200, v25
	v_fmac_f32_e32 v170, v200, v26
	v_fmac_f32_e32 v171, v200, v27
	v_fmac_f32_e32 v172, v200, v28
	v_fmac_f32_e32 v173, v200, v29
	v_fmac_f32_e32 v174, v200, v30
	v_fmac_f32_e32 v175, v200, v31
	v_add_f32_e32 v194, v194, v196
	v_add_u32_e32 v195, s42, v195
	global_load_dwordx4 v[16:19], v195, s[20:21]
	global_load_dwordx4 v[20:23], v195, s[20:21] offset:256
	global_load_dwordx4 v[24:27], v195, s[24:25]
	global_load_dwordx4 v[28:31], v195, s[24:25] offset:256
	s_waitcnt vmcnt(28)
	v_fma_f32 v197, v160, v32, v194
	v_fmac_f32_e32 v197, v161, v33
	v_fmac_f32_e32 v197, v162, v34
	v_fmac_f32_e32 v197, v163, v35
	v_fmac_f32_e32 v197, v164, v36
	v_fmac_f32_e32 v197, v165, v37
	v_fmac_f32_e32 v197, v166, v38
	v_fmac_f32_e32 v197, v167, v39
	s_nop 1
	v_add_f32_dpp v197, v197, v197 row_ror:8 row_mask:0xf bank_mask:0xf
	s_nop 1
	v_add_f32_dpp v197, v197, v197 row_ror:4 row_mask:0xf bank_mask:0xf
	s_nop 1
	v_add_f32_dpp v197, v197, v197 row_ror:2 row_mask:0xf bank_mask:0xf
	s_nop 1
	v_add_f32_dpp v197, v197, v197 row_ror:1 row_mask:0xf bank_mask:0xf
	v_max_f32_e32 v198, v192, v197
	v_sub_f32_e32 v199, v192, v198
	v_sub_f32_e32 v200, v197, v198
	v_exp_f32_e32 v199, v199
	v_exp_f32_e32 v200, v200
	v_mov_b32_e32 v192, v198
	v_fma_f32 v193, v193, v199, v200
	v_mul_f32_e32 v168, v168, v199
	v_mul_f32_e32 v169, v169, v199
	v_mul_f32_e32 v170, v170, v199
	v_mul_f32_e32 v171, v171, v199
	v_mul_f32_e32 v172, v172, v199
	v_mul_f32_e32 v173, v173, v199
	v_mul_f32_e32 v174, v174, v199
	v_mul_f32_e32 v175, v175, v199
	v_fmac_f32_e32 v168, v200, v40
	v_fmac_f32_e32 v169, v200, v41
	v_fmac_f32_e32 v170, v200, v42
	v_fmac_f32_e32 v171, v200, v43
	v_fmac_f32_e32 v172, v200, v44
	v_fmac_f32_e32 v173, v200, v45
	v_fmac_f32_e32 v174, v200, v46
	v_fmac_f32_e32 v175, v200, v47
	v_add_f32_e32 v194, v194, v196
	v_add_u32_e32 v195, s42, v195
	global_load_dwordx4 v[32:35], v195, s[20:21]
	global_load_dwordx4 v[36:39], v195, s[20:21] offset:256
	global_load_dwordx4 v[40:43], v195, s[24:25]
	global_load_dwordx4 v[44:47], v195, s[24:25] offset:256
	s_waitcnt vmcnt(28)
	v_fma_f32 v197, v160, v48, v194
	v_fmac_f32_e32 v197, v161, v49
	v_fmac_f32_e32 v197, v162, v50
	v_fmac_f32_e32 v197, v163, v51
	v_fmac_f32_e32 v197, v164, v52
	v_fmac_f32_e32 v197, v165, v53
	v_fmac_f32_e32 v197, v166, v54
	v_fmac_f32_e32 v197, v167, v55
	s_nop 1
	v_add_f32_dpp v197, v197, v197 row_ror:8 row_mask:0xf bank_mask:0xf
	s_nop 1
	v_add_f32_dpp v197, v197, v197 row_ror:4 row_mask:0xf bank_mask:0xf
	s_nop 1
	v_add_f32_dpp v197, v197, v197 row_ror:2 row_mask:0xf bank_mask:0xf
	s_nop 1
	v_add_f32_dpp v197, v197, v197 row_ror:1 row_mask:0xf bank_mask:0xf
	v_max_f32_e32 v198, v192, v197
	v_sub_f32_e32 v199, v192, v198
	v_sub_f32_e32 v200, v197, v198
	v_exp_f32_e32 v199, v199
	v_exp_f32_e32 v200, v200
	v_mov_b32_e32 v192, v198
	v_fma_f32 v193, v193, v199, v200
	v_mul_f32_e32 v168, v168, v199
	v_mul_f32_e32 v169, v169, v199
	v_mul_f32_e32 v170, v170, v199
	v_mul_f32_e32 v171, v171, v199
	v_mul_f32_e32 v172, v172, v199
	v_mul_f32_e32 v173, v173, v199
	v_mul_f32_e32 v174, v174, v199
	v_mul_f32_e32 v175, v175, v199
	v_fmac_f32_e32 v168, v200, v56
	v_fmac_f32_e32 v169, v200, v57
	v_fmac_f32_e32 v170, v200, v58
	v_fmac_f32_e32 v171, v200, v59
	v_fmac_f32_e32 v172, v200, v60
	v_fmac_f32_e32 v173, v200, v61
	v_fmac_f32_e32 v174, v200, v62
	v_fmac_f32_e32 v175, v200, v63
	v_add_f32_e32 v194, v194, v196
	v_add_u32_e32 v195, s42, v195
	global_load_dwordx4 v[48:51], v195, s[20:21]
	global_load_dwordx4 v[52:55], v195, s[20:21] offset:256
	global_load_dwordx4 v[56:59], v195, s[24:25]
	global_load_dwordx4 v[60:63], v195, s[24:25] offset:256
	s_waitcnt vmcnt(28)
	v_fma_f32 v197, v160, v64, v194
	v_fmac_f32_e32 v197, v161, v65
	v_fmac_f32_e32 v197, v162, v66
	v_fmac_f32_e32 v197, v163, v67
	v_fmac_f32_e32 v197, v164, v68
	v_fmac_f32_e32 v197, v165, v69
	v_fmac_f32_e32 v197, v166, v70
	v_fmac_f32_e32 v197, v167, v71
	s_nop 1
	v_add_f32_dpp v197, v197, v197 row_ror:8 row_mask:0xf bank_mask:0xf
	s_nop 1
	v_add_f32_dpp v197, v197, v197 row_ror:4 row_mask:0xf bank_mask:0xf
	s_nop 1
	v_add_f32_dpp v197, v197, v197 row_ror:2 row_mask:0xf bank_mask:0xf
	s_nop 1
	v_add_f32_dpp v197, v197, v197 row_ror:1 row_mask:0xf bank_mask:0xf
	v_max_f32_e32 v198, v192, v197
	v_sub_f32_e32 v199, v192, v198
	v_sub_f32_e32 v200, v197, v198
	v_exp_f32_e32 v199, v199
	v_exp_f32_e32 v200, v200
	v_mov_b32_e32 v192, v198
	v_fma_f32 v193, v193, v199, v200
	v_mul_f32_e32 v168, v168, v199
	v_mul_f32_e32 v169, v169, v199
	v_mul_f32_e32 v170, v170, v199
	v_mul_f32_e32 v171, v171, v199
	v_mul_f32_e32 v172, v172, v199
	v_mul_f32_e32 v173, v173, v199
	v_mul_f32_e32 v174, v174, v199
	v_mul_f32_e32 v175, v175, v199
	v_fmac_f32_e32 v168, v200, v72
	v_fmac_f32_e32 v169, v200, v73
	v_fmac_f32_e32 v170, v200, v74
	v_fmac_f32_e32 v171, v200, v75
	v_fmac_f32_e32 v172, v200, v76
	v_fmac_f32_e32 v173, v200, v77
	v_fmac_f32_e32 v174, v200, v78
	v_fmac_f32_e32 v175, v200, v79
	v_add_f32_e32 v194, v194, v196
	v_add_u32_e32 v195, s42, v195
	global_load_dwordx4 v[64:67], v195, s[20:21]
	global_load_dwordx4 v[68:71], v195, s[20:21] offset:256
	global_load_dwordx4 v[72:75], v195, s[24:25]
	global_load_dwordx4 v[76:79], v195, s[24:25] offset:256
	s_waitcnt vmcnt(28)
; __device__ __forceinline__ float fexp2(float x) { return __builtin_amdgcn_exp2f(x); }
; __device__ __forceinline__ void attn_sample_item(const P& p, int wi, int lane) {
;     ...
;         for (int jj = 0; jj < 33; ++jj) {
;             const int j = 4 * jj + kg; const bool valid = j <= 128; const int jc = valid ? j : 128;
;             const int idx = 2048 + i - d * jc;
;             f32x4 k0, k1, v0, v1;
;             if (idx < 2048) { const size_t off = (((size_t)bs * 2048 + idx) * 8 + h) * 128 + 8 * li;
;                 k0 = __builtin_nontemporal_load((const f32x4*)(p.cache_k + off)); k1 = __builtin_nontemporal_load((const f32x4*)(p.cache_k + off + 4)); v0 = __builtin_nontemporal_load((const f32x4*)(p.cache_v + off)); v1 = __builtin_nontemporal_load((const f32x4*)(p.cache_v + off + 4)); }
;             else { const int nr = bs * 4 + (idx - 2048); const float rsn = rstd1[TP + nr]; const int c0 = 4096 + h * 128 + 8 * li;
;                 k0 = acc1_4(ACC1, nr, c0) * rsn; k1 = acc1_4(ACC1, nr, c0 + 4) * rsn; v0 = acc1_4(ACC1, nr, c0 + 1024) * rsn; v1 = acc1_4(ACC1, nr, c0 + 1028) * rsn; }
;             float dot = (q[0] * k0[0] + q[1] * k0[1]) + (q[2] * k0[2] + q[3] * k0[3]) + (q[4] * k1[0] + q[5] * k1[1]) + (q[6] * k1[2] + q[7] * k1[3]);
;             dot += __shfl_xor(dot, 1); dot += __shfl_xor(dot, 2); dot += __shfl_xor(dot, 4); dot += __shfl_xor(dot, 8);
;             const float s = valid ? dot - sl * (float)(d * j) : -INFINITY;
;             const float mn = fmaxf(m, s), sc = fexp2(m - mn), pe = fexp2(s - mn);
;             l = l * sc + pe;
;             acc[0] = acc[0] * sc + pe * v0[0]; acc[1] = acc[1] * sc + pe * v0[1]; acc[2] = acc[2] * sc + pe * v0[2]; acc[3] = acc[3] * sc + pe * v0[3];
;             acc[4] = acc[4] * sc + pe * v1[0]; acc[5] = acc[5] * sc + pe * v1[1]; acc[6] = acc[6] * sc + pe * v1[2]; acc[7] = acc[7] * sc + pe * v1[3];
;             m = mn;
;         }
	v_fma_f32 v197, v160, v80, v194
	v_fmac_f32_e32 v197, v161, v81
	v_fmac_f32_e32 v197, v162, v82
	v_fmac_f32_e32 v197, v163, v83
	v_fmac_f32_e32 v197, v164, v84
	v_fmac_f32_e32 v197, v165, v85
	v_fmac_f32_e32 v197, v166, v86
	v_fmac_f32_e32 v197, v167, v87
	s_nop 1
	v_add_f32_dpp v197, v197, v197 row_ror:8 row_mask:0xf bank_mask:0xf
	s_nop 1
	v_add_f32_dpp v197, v197, v197 row_ror:4 row_mask:0xf bank_mask:0xf
	s_nop 1
	v_add_f32_dpp v197, v197, v197 row_ror:2 row_mask:0xf bank_mask:0xf
	s_nop 1
	v_add_f32_dpp v197, v197, v197 row_ror:1 row_mask:0xf bank_mask:0xf
	v_max_f32_e32 v198, v192, v197
	v_sub_f32_e32 v199, v192, v198
	v_sub_f32_e32 v200, v197, v198
	v_exp_f32_e32 v199, v199
	v_exp_f32_e32 v200, v200
	v_mov_b32_e32 v192, v198
	v_fma_f32 v193, v193, v199, v200
	v_mul_f32_e32 v168, v168, v199
	v_mul_f32_e32 v169, v169, v199
	v_mul_f32_e32 v170, v170, v199
	v_mul_f32_e32 v171, v171, v199
	v_mul_f32_e32 v172, v172, v199
	v_mul_f32_e32 v173, v173, v199
	v_mul_f32_e32 v174, v174, v199
	v_mul_f32_e32 v175, v175, v199
	v_fmac_f32_e32 v168, v200, v88
	v_fmac_f32_e32 v169, v200, v89
	v_fmac_f32_e32 v170, v200, v90
	v_fmac_f32_e32 v171, v200, v91
	v_fmac_f32_e32 v172, v200, v92
	v_fmac_f32_e32 v173, v200, v93
	v_fmac_f32_e32 v174, v200, v94
	v_fmac_f32_e32 v175, v200, v95
	v_add_f32_e32 v194, v194, v196
	v_add_u32_e32 v195, s42, v195
	global_load_dwordx4 v[80:83], v195, s[20:21]
	global_load_dwordx4 v[84:87], v195, s[20:21] offset:256
	global_load_dwordx4 v[88:91], v195, s[24:25]
	global_load_dwordx4 v[92:95], v195, s[24:25] offset:256
	s_waitcnt vmcnt(28)
	v_fma_f32 v197, v160, v96, v194
	v_fmac_f32_e32 v197, v161, v97
	v_fmac_f32_e32 v197, v162, v98
	v_fmac_f32_e32 v197, v163, v99
	v_fmac_f32_e32 v197, v164, v100
	v_fmac_f32_e32 v197, v165, v101
	v_fmac_f32_e32 v197, v166, v102
	v_fmac_f32_e32 v197, v167, v103
	s_nop 1
	v_add_f32_dpp v197, v197, v197 row_ror:8 row_mask:0xf bank_mask:0xf
	s_nop 1
	v_add_f32_dpp v197, v197, v197 row_ror:4 row_mask:0xf bank_mask:0xf
	s_nop 1
	v_add_f32_dpp v197, v197, v197 row_ror:2 row_mask:0xf bank_mask:0xf
	s_nop 1
	v_add_f32_dpp v197, v197, v197 row_ror:1 row_mask:0xf bank_mask:0xf
	v_max_f32_e32 v198, v192, v197
	v_sub_f32_e32 v199, v192, v198
	v_sub_f32_e32 v200, v197, v198
	v_exp_f32_e32 v199, v199
	v_exp_f32_e32 v200, v200
	v_mov_b32_e32 v192, v198
	v_fma_f32 v193, v193, v199, v200
	v_mul_f32_e32 v168, v168, v199
	v_mul_f32_e32 v169, v169, v199
	v_mul_f32_e32 v170, v170, v199
	v_mul_f32_e32 v171, v171, v199
	v_mul_f32_e32 v172, v172, v199
	v_mul_f32_e32 v173, v173, v199
	v_mul_f32_e32 v174, v174, v199
	v_mul_f32_e32 v175, v175, v199
	v_fmac_f32_e32 v168, v200, v104
	v_fmac_f32_e32 v169, v200, v105
	v_fmac_f32_e32 v170, v200, v106
	v_fmac_f32_e32 v171, v200, v107
	v_fmac_f32_e32 v172, v200, v108
	v_fmac_f32_e32 v173, v200, v109
	v_fmac_f32_e32 v174, v200, v110
	v_fmac_f32_e32 v175, v200, v111
	v_add_f32_e32 v194, v194, v196
	v_add_u32_e32 v195, s42, v195
	global_load_dwordx4 v[96:99], v195, s[20:21]
	global_load_dwordx4 v[100:103], v195, s[20:21] offset:256
	global_load_dwordx4 v[104:107], v195, s[24:25]
	global_load_dwordx4 v[108:111], v195, s[24:25] offset:256
	s_waitcnt vmcnt(28)
	v_fma_f32 v197, v160, v112, v194
	v_fmac_f32_e32 v197, v161, v113
	v_fmac_f32_e32 v197, v162, v114
	v_fmac_f32_e32 v197, v163, v115
	v_fmac_f32_e32 v197, v164, v116
	v_fmac_f32_e32 v197, v165, v117
	v_fmac_f32_e32 v197, v166, v118
	v_fmac_f32_e32 v197, v167, v119
	s_nop 1
	v_add_f32_dpp v197, v197, v197 row_ror:8 row_mask:0xf bank_mask:0xf
	s_nop 1
	v_add_f32_dpp v197, v197, v197 row_ror:4 row_mask:0xf bank_mask:0xf
	s_nop 1
	v_add_f32_dpp v197, v197, v197 row_ror:2 row_mask:0xf bank_mask:0xf
	s_nop 1
	v_add_f32_dpp v197, v197, v197 row_ror:1 row_mask:0xf bank_mask:0xf
	v_max_f32_e32 v198, v192, v197
	v_sub_f32_e32 v199, v192, v198
	v_sub_f32_e32 v200, v197, v198
	v_exp_f32_e32 v199, v199
	v_exp_f32_e32 v200, v200
	v_mov_b32_e32 v192, v198
	v_fma_f32 v193, v193, v199, v200
	v_mul_f32_e32 v168, v168, v199
	v_mul_f32_e32 v169, v169, v199
	v_mul_f32_e32 v170, v170, v199
	v_mul_f32_e32 v171, v171, v199
	v_mul_f32_e32 v172, v172, v199
	v_mul_f32_e32 v173, v173, v199
	v_mul_f32_e32 v174, v174, v199
	v_mul_f32_e32 v175, v175, v199
	v_fmac_f32_e32 v168, v200, v120
	v_fmac_f32_e32 v169, v200, v121
	v_fmac_f32_e32 v170, v200, v122
	v_fmac_f32_e32 v171, v200, v123
	v_fmac_f32_e32 v172, v200, v124
	v_fmac_f32_e32 v173, v200, v125
	v_fmac_f32_e32 v174, v200, v126
	v_fmac_f32_e32 v175, v200, v127
	v_add_f32_e32 v194, v194, v196
	v_add_u32_e32 v195, s42, v195
	global_load_dwordx4 v[112:115], v195, s[20:21]
	global_load_dwordx4 v[116:119], v195, s[20:21] offset:256
	global_load_dwordx4 v[120:123], v195, s[24:25]
	global_load_dwordx4 v[124:127], v195, s[24:25] offset:256
	s_add_u32 s33, s33, 1
	s_cmp_lt_u32 s33, 3
	s_cbranch_scc1 .Las_tripA

; __device__ __forceinline__ float fexp2(float x) { return __builtin_amdgcn_exp2f(x); }
; __device__ __forceinline__ void attn_sample_item(const P& p, int wi, int lane) {
;     ...
;         for (int jj = 0; jj < 33; ++jj) {
;             const int j = 4 * jj + kg; const bool valid = j <= 128; const int jc = valid ? j : 128;
;             const int idx = 2048 + i - d * jc;
;             f32x4 k0, k1, v0, v1;
;             if (idx < 2048) { const size_t off = (((size_t)bs * 2048 + idx) * 8 + h) * 128 + 8 * li;
;                 k0 = __builtin_nontemporal_load((const f32x4*)(p.cache_k + off)); k1 = __builtin_nontemporal_load((const f32x4*)(p.cache_k + off + 4)); v0 = __builtin_nontemporal_load((const f32x4*)(p.cache_v + off)); v1 = __builtin_nontemporal_load((const f32x4*)(p.cache_v + off + 4)); }
;             else { const int nr = bs * 4 + (idx - 2048); const float rsn = rstd1[TP + nr]; const int c0 = 4096 + h * 128 + 8 * li;
;                 k0 = acc1_4(ACC1, nr, c0) * rsn; k1 = acc1_4(ACC1, nr, c0 + 4) * rsn; v0 = acc1_4(ACC1, nr, c0 + 1024) * rsn; v1 = acc1_4(ACC1, nr, c0 + 1028) * rsn; }
;             float dot = (q[0] * k0[0] + q[1] * k0[1]) + (q[2] * k0[2] + q[3] * k0[3]) + (q[4] * k1[0] + q[5] * k1[1]) + (q[6] * k1[2] + q[7] * k1[3]);
;             dot += __shfl_xor(dot, 1); dot += __shfl_xor(dot, 2); dot += __shfl_xor(dot, 4); dot += __shfl_xor(dot, 8);
;             const float s = valid ? dot - sl * (float)(d * j) : -INFINITY;
;             const float mn = fmaxf(m, s), sc = fexp2(m - mn), pe = fexp2(s - mn);
;             l = l * sc + pe;
;             acc[0] = acc[0] * sc + pe * v0[0]; acc[1] = acc[1] * sc + pe * v0[1]; acc[2] = acc[2] * sc + pe * v0[2]; acc[3] = acc[3] * sc + pe * v0[3];
;             acc[4] = acc[4] * sc + pe * v1[0]; acc[5] = acc[5] * sc + pe * v1[1]; acc[6] = acc[6] * sc + pe * v1[2]; acc[7] = acc[7] * sc + pe * v1[3];
;             m = mn;
;         }
.Las_sw4:
	s_waitcnt vmcnt(28)
	v_fma_f32 v197, v160, v0, v194
	v_fmac_f32_e32 v197, v161, v1
	v_fmac_f32_e32 v197, v162, v2
	v_fmac_f32_e32 v197, v163, v3
	v_fmac_f32_e32 v197, v164, v4
	v_fmac_f32_e32 v197, v165, v5
	v_fmac_f32_e32 v197, v166, v6
	v_fmac_f32_e32 v197, v167, v7
	s_nop 1
	v_add_f32_dpp v197, v197, v197 row_ror:8 row_mask:0xf bank_mask:0xf
	s_nop 1
	v_add_f32_dpp v197, v197, v197 row_ror:4 row_mask:0xf bank_mask:0xf
	s_nop 1
	v_add_f32_dpp v197, v197, v197 row_ror:2 row_mask:0xf bank_mask:0xf
	s_nop 1
	v_add_f32_dpp v197, v197, v197 row_ror:1 row_mask:0xf bank_mask:0xf
	v_max_f32_e32 v198, v192, v197
	v_sub_f32_e32 v199, v192, v198
	v_sub_f32_e32 v200, v197, v198
	v_exp_f32_e32 v199, v199
	v_exp_f32_e32 v200, v200
	v_mov_b32_e32 v192, v198
	v_fma_f32 v193, v193, v199, v200
	v_mul_f32_e32 v168, v168, v199
	v_mul_f32_e32 v169, v169, v199
	v_mul_f32_e32 v170, v170, v199
	v_mul_f32_e32 v171, v171, v199
	v_mul_f32_e32 v172, v172, v199
	v_mul_f32_e32 v173, v173, v199
	v_mul_f32_e32 v174, v174, v199
	v_mul_f32_e32 v175, v175, v199
	v_fmac_f32_e32 v168, v200, v8
	v_fmac_f32_e32 v169, v200, v9
	v_fmac_f32_e32 v170, v200, v10
	v_fmac_f32_e32 v171, v200, v11
	v_fmac_f32_e32 v172, v200, v12
	v_fmac_f32_e32 v173, v200, v13
	v_fmac_f32_e32 v174, v200, v14
	v_fmac_f32_e32 v175, v200, v15
	v_add_f32_e32 v194, v194, v196
	v_add_u32_e32 v195, s42, v195
	global_load_dwordx4 v[0:3], v195, s[20:21] nt
	global_load_dwordx4 v[4:7], v195, s[20:21] offset:256 nt
	global_load_dwordx4 v[8:11], v195, s[24:25] nt
	global_load_dwordx4 v[12:15], v195, s[24:25] offset:256 nt
	s_waitcnt vmcnt(28)
	v_fma_f32 v197, v160, v16, v194
	v_fmac_f32_e32 v197, v161, v17
	v_fmac_f32_e32 v197, v162, v18
	v_fmac_f32_e32 v197, v163, v19
	v_fmac_f32_e32 v197, v164, v20
	v_fmac_f32_e32 v197, v165, v21
	v_fmac_f32_e32 v197, v166, v22
	v_fmac_f32_e32 v197, v167, v23
	s_nop 1
	v_add_f32_dpp v197, v197, v197 row_ror:8 row_mask:0xf bank_mask:0xf
	s_nop 1
	v_add_f32_dpp v197, v197, v197 row_ror:4 row_mask:0xf bank_mask:0xf
	s_nop 1
	v_add_f32_dpp v197, v197, v197 row_ror:2 row_mask:0xf bank_mask:0xf
	s_nop 1
	v_add_f32_dpp v197, v197, v197 row_ror:1 row_mask:0xf bank_mask:0xf
	v_max_f32_e32 v198, v192, v197
	v_sub_f32_e32 v199, v192, v198
	v_sub_f32_e32 v200, v197, v198
	v_exp_f32_e32 v199, v199
	v_exp_f32_e32 v200, v200
	v_mov_b32_e32 v192, v198
	v_fma_f32 v193, v193, v199, v200
	v_mul_f32_e32 v168, v168, v199
	v_mul_f32_e32 v169, v169, v199
	v_mul_f32_e32 v170, v170, v199
	v_mul_f32_e32 v171, v171, v199
	v_mul_f32_e32 v172, v172, v199
	v_mul_f32_e32 v173, v173, v199
	v_mul_f32_e32 v174, v174, v199
	v_mul_f32_e32 v175, v175, v199
	v_fmac_f32_e32 v168, v200, v24
	v_fmac_f32_e32 v169, v200, v25
	v_fmac_f32_e32 v170, v200, v26
	v_fmac_f32_e32 v171, v200, v27
	v_fmac_f32_e32 v172, v200, v28
	v_fmac_f32_e32 v173, v200, v29
	v_fmac_f32_e32 v174, v200, v30
	v_fmac_f32_e32 v175, v200, v31
	v_add_f32_e32 v194, v194, v196
	v_add_u32_e32 v195, s42, v195
	global_load_dwordx4 v[16:19], v195, s[20:21] nt
	global_load_dwordx4 v[20:23], v195, s[20:21] offset:256 nt
	global_load_dwordx4 v[24:27], v195, s[24:25] nt
	global_load_dwordx4 v[28:31], v195, s[24:25] offset:256 nt
	s_waitcnt vmcnt(28)
	v_fma_f32 v197, v160, v32, v194
	v_fmac_f32_e32 v197, v161, v33
	v_fmac_f32_e32 v197, v162, v34
	v_fmac_f32_e32 v197, v163, v35
	v_fmac_f32_e32 v197, v164, v36
	v_fmac_f32_e32 v197, v165, v37
	v_fmac_f32_e32 v197, v166, v38
	v_fmac_f32_e32 v197, v167, v39
	s_nop 1
	v_add_f32_dpp v197, v197, v197 row_ror:8 row_mask:0xf bank_mask:0xf
	s_nop 1
	v_add_f32_dpp v197, v197, v197 row_ror:4 row_mask:0xf bank_mask:0xf
	s_nop 1
	v_add_f32_dpp v197, v197, v197 row_ror:2 row_mask:0xf bank_mask:0xf
	s_nop 1
	v_add_f32_dpp v197, v197, v197 row_ror:1 row_mask:0xf bank_mask:0xf
	v_max_f32_e32 v198, v192, v197
	v_sub_f32_e32 v199, v192, v198
	v_sub_f32_e32 v200, v197, v198
	v_exp_f32_e32 v199, v199
	v_exp_f32_e32 v200, v200
	v_mov_b32_e32 v192, v198
	v_fma_f32 v193, v193, v199, v200
	v_mul_f32_e32 v168, v168, v199
	v_mul_f32_e32 v169, v169, v199
	v_mul_f32_e32 v170, v170, v199
	v_mul_f32_e32 v171, v171, v199
	v_mul_f32_e32 v172, v172, v199
	v_mul_f32_e32 v173, v173, v199
	v_mul_f32_e32 v174, v174, v199
	v_mul_f32_e32 v175, v175, v199
	v_fmac_f32_e32 v168, v200, v40
	v_fmac_f32_e32 v169, v200, v41
	v_fmac_f32_e32 v170, v200, v42
	v_fmac_f32_e32 v171, v200, v43
	v_fmac_f32_e32 v172, v200, v44
	v_fmac_f32_e32 v173, v200, v45
	v_fmac_f32_e32 v174, v200, v46
	v_fmac_f32_e32 v175, v200, v47
	v_add_f32_e32 v194, v194, v196
	v_add_u32_e32 v195, s42, v195
	global_load_dwordx4 v[32:35], v195, s[20:21] nt
	global_load_dwordx4 v[36:39], v195, s[20:21] offset:256 nt
	global_load_dwordx4 v[40:43], v195, s[24:25] nt
	global_load_dwordx4 v[44:47], v195, s[24:25] offset:256 nt
	s_waitcnt vmcnt(28)
	v_fma_f32 v197, v160, v48, v194
	v_fmac_f32_e32 v197, v161, v49
	v_fmac_f32_e32 v197, v162, v50
	v_fmac_f32_e32 v197, v163, v51
	v_fmac_f32_e32 v197, v164, v52
	v_fmac_f32_e32 v197, v165, v53
	v_fmac_f32_e32 v197, v166, v54
	v_fmac_f32_e32 v197, v167, v55
	s_nop 1
	v_add_f32_dpp v197, v197, v197 row_ror:8 row_mask:0xf bank_mask:0xf
	s_nop 1
	v_add_f32_dpp v197, v197, v197 row_ror:4 row_mask:0xf bank_mask:0xf
	s_nop 1
	v_add_f32_dpp v197, v197, v197 row_ror:2 row_mask:0xf bank_mask:0xf
	s_nop 1
	v_add_f32_dpp v197, v197, v197 row_ror:1 row_mask:0xf bank_mask:0xf
	v_max_f32_e32 v198, v192, v197
	v_sub_f32_e32 v199, v192, v198
	v_sub_f32_e32 v200, v197, v198
	v_exp_f32_e32 v199, v199
	v_exp_f32_e32 v200, v200
	v_mov_b32_e32 v192, v198
	v_fma_f32 v193, v193, v199, v200
	v_mul_f32_e32 v168, v168, v199
	v_mul_f32_e32 v169, v169, v199
	v_mul_f32_e32 v170, v170, v199
	v_mul_f32_e32 v171, v171, v199
	v_mul_f32_e32 v172, v172, v199
	v_mul_f32_e32 v173, v173, v199
	v_mul_f32_e32 v174, v174, v199
	v_mul_f32_e32 v175, v175, v199
	v_fmac_f32_e32 v168, v200, v56
	v_fmac_f32_e32 v169, v200, v57
	v_fmac_f32_e32 v170, v200, v58
	v_fmac_f32_e32 v171, v200, v59
	v_fmac_f32_e32 v172, v200, v60
	v_fmac_f32_e32 v173, v200, v61
	v_fmac_f32_e32 v174, v200, v62
	v_fmac_f32_e32 v175, v200, v63
	v_add_f32_e32 v194, v194, v196
	v_add_u32_e32 v195, s42, v195
	global_load_dwordx4 v[48:51], v195, s[20:21] nt
	global_load_dwordx4 v[52:55], v195, s[20:21] offset:256 nt
	global_load_dwordx4 v[56:59], v195, s[24:25] nt
	global_load_dwordx4 v[60:63], v195, s[24:25] offset:256 nt
	s_waitcnt vmcnt(28)
; __device__ __forceinline__ float fexp2(float x) { return __builtin_amdgcn_exp2f(x); }
; __device__ __forceinline__ void attn_sample_item(const P& p, int wi, int lane) {
;     ...
;         for (int jj = 0; jj < 33; ++jj) {
;             const int j = 4 * jj + kg; const bool valid = j <= 128; const int jc = valid ? j : 128;
;             const int idx = 2048 + i - d * jc;
;             f32x4 k0, k1, v0, v1;
;             if (idx < 2048) { const size_t off = (((size_t)bs * 2048 + idx) * 8 + h) * 128 + 8 * li;
;                 k0 = __builtin_nontemporal_load((const f32x4*)(p.cache_k + off)); k1 = __builtin_nontemporal_load((const f32x4*)(p.cache_k + off + 4)); v0 = __builtin_nontemporal_load((const f32x4*)(p.cache_v + off)); v1 = __builtin_nontemporal_load((const f32x4*)(p.cache_v + off + 4)); }
;             else { const int nr = bs * 4 + (idx - 2048); const float rsn = rstd1[TP + nr]; const int c0 = 4096 + h * 128 + 8 * li;
;                 k0 = acc1_4(ACC1, nr, c0) * rsn; k1 = acc1_4(ACC1, nr, c0 + 4) * rsn; v0 = acc1_4(ACC1, nr, c0 + 1024) * rsn; v1 = acc1_4(ACC1, nr, c0 + 1028) * rsn; }
;             float dot = (q[0] * k0[0] + q[1] * k0[1]) + (q[2] * k0[2] + q[3] * k0[3]) + (q[4] * k1[0] + q[5] * k1[1]) + (q[6] * k1[2] + q[7] * k1[3]);
;             dot += __shfl_xor(dot, 1); dot += __shfl_xor(dot, 2); dot += __shfl_xor(dot, 4); dot += __shfl_xor(dot, 8);
;             const float s = valid ? dot - sl * (float)(d * j) : -INFINITY;
;             const float mn = fmaxf(m, s), sc = fexp2(m - mn), pe = fexp2(s - mn);
;             l = l * sc + pe;
;             acc[0] = acc[0] * sc + pe * v0[0]; acc[1] = acc[1] * sc + pe * v0[1]; acc[2] = acc[2] * sc + pe * v0[2]; acc[3] = acc[3] * sc + pe * v0[3];
;             acc[4] = acc[4] * sc + pe * v1[0]; acc[5] = acc[5] * sc + pe * v1[1]; acc[6] = acc[6] * sc + pe * v1[2]; acc[7] = acc[7] * sc + pe * v1[3];
;             m = mn;
;         }
	v_fma_f32 v197, v160, v64, v194
	v_fmac_f32_e32 v197, v161, v65
	v_fmac_f32_e32 v197, v162, v66
	v_fmac_f32_e32 v197, v163, v67
	v_fmac_f32_e32 v197, v164, v68
	v_fmac_f32_e32 v197, v165, v69
	v_fmac_f32_e32 v197, v166, v70
	v_fmac_f32_e32 v197, v167, v71
	s_nop 1
	v_add_f32_dpp v197, v197, v197 row_ror:8 row_mask:0xf bank_mask:0xf
	s_nop 1
	v_add_f32_dpp v197, v197, v197 row_ror:4 row_mask:0xf bank_mask:0xf
	s_nop 1
	v_add_f32_dpp v197, v197, v197 row_ror:2 row_mask:0xf bank_mask:0xf
	s_nop 1
	v_add_f32_dpp v197, v197, v197 row_ror:1 row_mask:0xf bank_mask:0xf
	v_max_f32_e32 v198, v192, v197
	v_sub_f32_e32 v199, v192, v198
	v_sub_f32_e32 v200, v197, v198
	v_exp_f32_e32 v199, v199
	v_exp_f32_e32 v200, v200
	v_mov_b32_e32 v192, v198
	v_fma_f32 v193, v193, v199, v200
	v_mul_f32_e32 v168, v168, v199
	v_mul_f32_e32 v169, v169, v199
	v_mul_f32_e32 v170, v170, v199
	v_mul_f32_e32 v171, v171, v199
	v_mul_f32_e32 v172, v172, v199
	v_mul_f32_e32 v173, v173, v199
	v_mul_f32_e32 v174, v174, v199
	v_mul_f32_e32 v175, v175, v199
	v_fmac_f32_e32 v168, v200, v72
	v_fmac_f32_e32 v169, v200, v73
	v_fmac_f32_e32 v170, v200, v74
	v_fmac_f32_e32 v171, v200, v75
	v_fmac_f32_e32 v172, v200, v76
	v_fmac_f32_e32 v173, v200, v77
	v_fmac_f32_e32 v174, v200, v78
	v_fmac_f32_e32 v175, v200, v79
	v_add_f32_e32 v194, v194, v196
	v_add_u32_e32 v195, s42, v195
	global_load_dwordx4 v[64:67], v195, s[20:21] nt
	global_load_dwordx4 v[68:71], v195, s[20:21] offset:256 nt
	global_load_dwordx4 v[72:75], v195, s[24:25] nt
	global_load_dwordx4 v[76:79], v195, s[24:25] offset:256 nt
	s_waitcnt vmcnt(28)
	v_fma_f32 v197, v160, v80, v194
	v_fmac_f32_e32 v197, v161, v81
	v_fmac_f32_e32 v197, v162, v82
	v_fmac_f32_e32 v197, v163, v83
	v_fmac_f32_e32 v197, v164, v84
	v_fmac_f32_e32 v197, v165, v85
	v_fmac_f32_e32 v197, v166, v86
	v_fmac_f32_e32 v197, v167, v87
	s_nop 1
	v_add_f32_dpp v197, v197, v197 row_ror:8 row_mask:0xf bank_mask:0xf
	s_nop 1
	v_add_f32_dpp v197, v197, v197 row_ror:4 row_mask:0xf bank_mask:0xf
	s_nop 1
	v_add_f32_dpp v197, v197, v197 row_ror:2 row_mask:0xf bank_mask:0xf
	s_nop 1
	v_add_f32_dpp v197, v197, v197 row_ror:1 row_mask:0xf bank_mask:0xf
	v_max_f32_e32 v198, v192, v197
	v_sub_f32_e32 v199, v192, v198
	v_sub_f32_e32 v200, v197, v198
	v_exp_f32_e32 v199, v199
	v_exp_f32_e32 v200, v200
	v_mov_b32_e32 v192, v198
	v_fma_f32 v193, v193, v199, v200
	v_mul_f32_e32 v168, v168, v199
	v_mul_f32_e32 v169, v169, v199
	v_mul_f32_e32 v170, v170, v199
	v_mul_f32_e32 v171, v171, v199
	v_mul_f32_e32 v172, v172, v199
	v_mul_f32_e32 v173, v173, v199
	v_mul_f32_e32 v174, v174, v199
	v_mul_f32_e32 v175, v175, v199
	v_fmac_f32_e32 v168, v200, v88
	v_fmac_f32_e32 v169, v200, v89
	v_fmac_f32_e32 v170, v200, v90
	v_fmac_f32_e32 v171, v200, v91
	v_fmac_f32_e32 v172, v200, v92
	v_fmac_f32_e32 v173, v200, v93
	v_fmac_f32_e32 v174, v200, v94
	v_fmac_f32_e32 v175, v200, v95
	v_add_f32_e32 v194, v194, v196
	v_add_u32_e32 v195, s42, v195
	global_load_dwordx4 v[80:83], v195, s[20:21] nt
	global_load_dwordx4 v[84:87], v195, s[20:21] offset:256 nt
	global_load_dwordx4 v[88:91], v195, s[24:25] nt
	global_load_dwordx4 v[92:95], v195, s[24:25] offset:256 nt
	s_waitcnt vmcnt(28)
	v_fma_f32 v197, v160, v96, v194
	v_fmac_f32_e32 v197, v161, v97
	v_fmac_f32_e32 v197, v162, v98
	v_fmac_f32_e32 v197, v163, v99
	v_fmac_f32_e32 v197, v164, v100
	v_fmac_f32_e32 v197, v165, v101
	v_fmac_f32_e32 v197, v166, v102
	v_fmac_f32_e32 v197, v167, v103
	s_nop 1
	v_add_f32_dpp v197, v197, v197 row_ror:8 row_mask:0xf bank_mask:0xf
	s_nop 1
	v_add_f32_dpp v197, v197, v197 row_ror:4 row_mask:0xf bank_mask:0xf
	s_nop 1
	v_add_f32_dpp v197, v197, v197 row_ror:2 row_mask:0xf bank_mask:0xf
	s_nop 1
	v_add_f32_dpp v197, v197, v197 row_ror:1 row_mask:0xf bank_mask:0xf
	v_max_f32_e32 v198, v192, v197
	v_sub_f32_e32 v199, v192, v198
	v_sub_f32_e32 v200, v197, v198
	v_exp_f32_e32 v199, v199
	v_exp_f32_e32 v200, v200
	v_mov_b32_e32 v192, v198
	v_fma_f32 v193, v193, v199, v200
	v_mul_f32_e32 v168, v168, v199
	v_mul_f32_e32 v169, v169, v199
	v_mul_f32_e32 v170, v170, v199
	v_mul_f32_e32 v171, v171, v199
	v_mul_f32_e32 v172, v172, v199
	v_mul_f32_e32 v173, v173, v199
	v_mul_f32_e32 v174, v174, v199
	v_mul_f32_e32 v175, v175, v199
	v_fmac_f32_e32 v168, v200, v104
	v_fmac_f32_e32 v169, v200, v105
	v_fmac_f32_e32 v170, v200, v106
	v_fmac_f32_e32 v171, v200, v107
	v_fmac_f32_e32 v172, v200, v108
	v_fmac_f32_e32 v173, v200, v109
	v_fmac_f32_e32 v174, v200, v110
	v_fmac_f32_e32 v175, v200, v111
	v_add_f32_e32 v194, v194, v196
	v_add_u32_e32 v195, s42, v195
	global_load_dwordx4 v[96:99], v195, s[20:21] nt
	global_load_dwordx4 v[100:103], v195, s[20:21] offset:256 nt
	global_load_dwordx4 v[104:107], v195, s[24:25] nt
	global_load_dwordx4 v[108:111], v195, s[24:25] offset:256 nt
	s_waitcnt vmcnt(28)
	v_fma_f32 v197, v160, v112, v194
	v_fmac_f32_e32 v197, v161, v113
	v_fmac_f32_e32 v197, v162, v114
	v_fmac_f32_e32 v197, v163, v115
	v_fmac_f32_e32 v197, v164, v116
	v_fmac_f32_e32 v197, v165, v117
	v_fmac_f32_e32 v197, v166, v118
	v_fmac_f32_e32 v197, v167, v119
	s_nop 1
	v_add_f32_dpp v197, v197, v197 row_ror:8 row_mask:0xf bank_mask:0xf
	s_nop 1
	v_add_f32_dpp v197, v197, v197 row_ror:4 row_mask:0xf bank_mask:0xf
	s_nop 1
	v_add_f32_dpp v197, v197, v197 row_ror:2 row_mask:0xf bank_mask:0xf
	s_nop 1
	v_add_f32_dpp v197, v197, v197 row_ror:1 row_mask:0xf bank_mask:0xf
	v_max_f32_e32 v198, v192, v197
	v_sub_f32_e32 v199, v192, v198
	v_sub_f32_e32 v200, v197, v198
	v_exp_f32_e32 v199, v199
	v_exp_f32_e32 v200, v200
	v_mov_b32_e32 v192, v198
	v_fma_f32 v193, v193, v199, v200
	v_mul_f32_e32 v168, v168, v199
	v_mul_f32_e32 v169, v169, v199
	v_mul_f32_e32 v170, v170, v199
	v_mul_f32_e32 v171, v171, v199
	v_mul_f32_e32 v172, v172, v199
	v_mul_f32_e32 v173, v173, v199
	v_mul_f32_e32 v174, v174, v199
	v_mul_f32_e32 v175, v175, v199
	v_fmac_f32_e32 v168, v200, v120
	v_fmac_f32_e32 v169, v200, v121
	v_fmac_f32_e32 v170, v200, v122
	v_fmac_f32_e32 v171, v200, v123
	v_fmac_f32_e32 v172, v200, v124
	v_fmac_f32_e32 v173, v200, v125
	v_fmac_f32_e32 v174, v200, v126
	v_fmac_f32_e32 v175, v200, v127
	v_add_f32_e32 v194, v194, v196
	v_add_u32_e32 v195, s42, v195
	global_load_dwordx4 v[112:115], v195, s[20:21] nt
	global_load_dwordx4 v[116:119], v195, s[20:21] offset:256 nt
	global_load_dwordx4 v[120:123], v195, s[24:25] nt
	global_load_dwordx4 v[124:127], v195, s[24:25] offset:256 nt
	s_add_u32 s33, s33, 1
	s_cmp_lt_u32 s33, 11
	s_cbranch_scc1 .Las_trip
; __device__ __forceinline__ float fexp2(float x) { return __builtin_amdgcn_exp2f(x); }
; __device__ __forceinline__ void attn_sample_item(const P& p, int wi, int lane) {
;     ...
;         for (int jj = 0; jj < 33; ++jj) {
;             const int j = 4 * jj + kg; const bool valid = j <= 128; const int jc = valid ? j : 128;
;             const int idx = 2048 + i - d * jc;
;             f32x4 k0, k1, v0, v1;
;             if (idx < 2048) { const size_t off = (((size_t)bs * 2048 + idx) * 8 + h) * 128 + 8 * li;
;                 k0 = __builtin_nontemporal_load((const f32x4*)(p.cache_k + off)); k1 = __builtin_nontemporal_load((const f32x4*)(p.cache_k + off + 4)); v0 = __builtin_nontemporal_load((const f32x4*)(p.cache_v + off)); v1 = __builtin_nontemporal_load((const f32x4*)(p.cache_v + off + 4)); }
;             else { const int nr = bs * 4 + (idx - 2048); const float rsn = rstd1[TP + nr]; const int c0 = 4096 + h * 128 + 8 * li;
;                 k0 = acc1_4(ACC1, nr, c0) * rsn; k1 = acc1_4(ACC1, nr, c0 + 4) * rsn; v0 = acc1_4(ACC1, nr, c0 + 1024) * rsn; v1 = acc1_4(ACC1, nr, c0 + 1028) * rsn; }
;             float dot = (q[0] * k0[0] + q[1] * k0[1]) + (q[2] * k0[2] + q[3] * k0[3]) + (q[4] * k1[0] + q[5] * k1[1]) + (q[6] * k1[2] + q[7] * k1[3]);
;             dot += __shfl_xor(dot, 1); dot += __shfl_xor(dot, 2); dot += __shfl_xor(dot, 4); dot += __shfl_xor(dot, 8);
;             const float s = valid ? dot - sl * (float)(d * j) : -INFINITY;
;             const float mn = fmaxf(m, s), sc = fexp2(m - mn), pe = fexp2(s - mn);
;             l = l * sc + pe;
;             acc[0] = acc[0] * sc + pe * v0[0]; acc[1] = acc[1] * sc + pe * v0[1]; acc[2] = acc[2] * sc + pe * v0[2]; acc[3] = acc[3] * sc + pe * v0[3];
;             acc[4] = acc[4] * sc + pe * v1[0]; acc[5] = acc[5] * sc + pe * v1[1]; acc[6] = acc[6] * sc + pe * v1[2]; acc[7] = acc[7] * sc + pe * v1[3];
;             m = mn;
;         }
	s_waitcnt vmcnt(28)
	v_fma_f32 v197, v160, v0, v194
	v_fmac_f32_e32 v197, v161, v1
	v_fmac_f32_e32 v197, v162, v2
	v_fmac_f32_e32 v197, v163, v3
	v_fmac_f32_e32 v197, v164, v4
	v_fmac_f32_e32 v197, v165, v5
	v_fmac_f32_e32 v197, v166, v6
	v_fmac_f32_e32 v197, v167, v7
	s_nop 1
	v_add_f32_dpp v197, v197, v197 row_ror:8 row_mask:0xf bank_mask:0xf
	s_nop 1
	v_add_f32_dpp v197, v197, v197 row_ror:4 row_mask:0xf bank_mask:0xf
	s_nop 1
	v_add_f32_dpp v197, v197, v197 row_ror:2 row_mask:0xf bank_mask:0xf
	s_nop 1
	v_add_f32_dpp v197, v197, v197 row_ror:1 row_mask:0xf bank_mask:0xf
	v_max_f32_e32 v198, v192, v197
	v_sub_f32_e32 v199, v192, v198
	v_sub_f32_e32 v200, v197, v198
	v_exp_f32_e32 v199, v199
	v_exp_f32_e32 v200, v200
	v_mov_b32_e32 v192, v198
	v_fma_f32 v193, v193, v199, v200
	v_mul_f32_e32 v168, v168, v199
	v_mul_f32_e32 v169, v169, v199
	v_mul_f32_e32 v170, v170, v199
	v_mul_f32_e32 v171, v171, v199
	v_mul_f32_e32 v172, v172, v199
	v_mul_f32_e32 v173, v173, v199
	v_mul_f32_e32 v174, v174, v199
	v_mul_f32_e32 v175, v175, v199
	v_fmac_f32_e32 v168, v200, v8
	v_fmac_f32_e32 v169, v200, v9
	v_fmac_f32_e32 v170, v200, v10
	v_fmac_f32_e32 v171, v200, v11
	v_fmac_f32_e32 v172, v200, v12
	v_fmac_f32_e32 v173, v200, v13
	v_fmac_f32_e32 v174, v200, v14
	v_fmac_f32_e32 v175, v200, v15
	v_add_f32_e32 v194, v194, v196
	s_waitcnt vmcnt(24)
	v_fma_f32 v197, v160, v16, v194
	v_fmac_f32_e32 v197, v161, v17
	v_fmac_f32_e32 v197, v162, v18
	v_fmac_f32_e32 v197, v163, v19
	v_fmac_f32_e32 v197, v164, v20
	v_fmac_f32_e32 v197, v165, v21
	v_fmac_f32_e32 v197, v166, v22
	v_fmac_f32_e32 v197, v167, v23
	s_nop 1
	v_add_f32_dpp v197, v197, v197 row_ror:8 row_mask:0xf bank_mask:0xf
	s_nop 1
	v_add_f32_dpp v197, v197, v197 row_ror:4 row_mask:0xf bank_mask:0xf
	s_nop 1
	v_add_f32_dpp v197, v197, v197 row_ror:2 row_mask:0xf bank_mask:0xf
	s_nop 1
	v_add_f32_dpp v197, v197, v197 row_ror:1 row_mask:0xf bank_mask:0xf
	v_max_f32_e32 v198, v192, v197
	v_sub_f32_e32 v199, v192, v198
	v_sub_f32_e32 v200, v197, v198
	v_exp_f32_e32 v199, v199
	v_exp_f32_e32 v200, v200
	v_mov_b32_e32 v192, v198
	v_fma_f32 v193, v193, v199, v200
	v_mul_f32_e32 v168, v168, v199
	v_mul_f32_e32 v169, v169, v199
	v_mul_f32_e32 v170, v170, v199
	v_mul_f32_e32 v171, v171, v199
	v_mul_f32_e32 v172, v172, v199
	v_mul_f32_e32 v173, v173, v199
	v_mul_f32_e32 v174, v174, v199
	v_mul_f32_e32 v175, v175, v199
	v_fmac_f32_e32 v168, v200, v24
	v_fmac_f32_e32 v169, v200, v25
	v_fmac_f32_e32 v170, v200, v26
	v_fmac_f32_e32 v171, v200, v27
	v_fmac_f32_e32 v172, v200, v28
	v_fmac_f32_e32 v173, v200, v29
	v_fmac_f32_e32 v174, v200, v30
	v_fmac_f32_e32 v175, v200, v31
	v_add_f32_e32 v194, v194, v196
	s_waitcnt vmcnt(20)
	v_fma_f32 v197, v160, v32, v194
	v_fmac_f32_e32 v197, v161, v33
	v_fmac_f32_e32 v197, v162, v34
	v_fmac_f32_e32 v197, v163, v35
	v_fmac_f32_e32 v197, v164, v36
	v_fmac_f32_e32 v197, v165, v37
	v_fmac_f32_e32 v197, v166, v38
	v_fmac_f32_e32 v197, v167, v39
	s_nop 1
	v_add_f32_dpp v197, v197, v197 row_ror:8 row_mask:0xf bank_mask:0xf
	s_nop 1
	v_add_f32_dpp v197, v197, v197 row_ror:4 row_mask:0xf bank_mask:0xf
	s_nop 1
	v_add_f32_dpp v197, v197, v197 row_ror:2 row_mask:0xf bank_mask:0xf
	s_nop 1
	v_add_f32_dpp v197, v197, v197 row_ror:1 row_mask:0xf bank_mask:0xf
	v_max_f32_e32 v198, v192, v197
	v_sub_f32_e32 v199, v192, v198
	v_sub_f32_e32 v200, v197, v198
	v_exp_f32_e32 v199, v199
	v_exp_f32_e32 v200, v200
	v_mov_b32_e32 v192, v198
	v_fma_f32 v193, v193, v199, v200
	v_mul_f32_e32 v168, v168, v199
	v_mul_f32_e32 v169, v169, v199
	v_mul_f32_e32 v170, v170, v199
	v_mul_f32_e32 v171, v171, v199
	v_mul_f32_e32 v172, v172, v199
	v_mul_f32_e32 v173, v173, v199
	v_mul_f32_e32 v174, v174, v199
	v_mul_f32_e32 v175, v175, v199
	v_fmac_f32_e32 v168, v200, v40
	v_fmac_f32_e32 v169, v200, v41
	v_fmac_f32_e32 v170, v200, v42
	v_fmac_f32_e32 v171, v200, v43
	v_fmac_f32_e32 v172, v200, v44
	v_fmac_f32_e32 v173, v200, v45
	v_fmac_f32_e32 v174, v200, v46
	v_fmac_f32_e32 v175, v200, v47
	v_add_f32_e32 v194, v194, v196
	s_waitcnt vmcnt(16)
	v_fma_f32 v197, v160, v48, v194
	v_fmac_f32_e32 v197, v161, v49
	v_fmac_f32_e32 v197, v162, v50
	v_fmac_f32_e32 v197, v163, v51
	v_fmac_f32_e32 v197, v164, v52
	v_fmac_f32_e32 v197, v165, v53
	v_fmac_f32_e32 v197, v166, v54
	v_fmac_f32_e32 v197, v167, v55
	s_nop 1
	v_add_f32_dpp v197, v197, v197 row_ror:8 row_mask:0xf bank_mask:0xf
	s_nop 1
	v_add_f32_dpp v197, v197, v197 row_ror:4 row_mask:0xf bank_mask:0xf
	s_nop 1
	v_add_f32_dpp v197, v197, v197 row_ror:2 row_mask:0xf bank_mask:0xf
	s_nop 1
	v_add_f32_dpp v197, v197, v197 row_ror:1 row_mask:0xf bank_mask:0xf
	v_max_f32_e32 v198, v192, v197
	v_sub_f32_e32 v199, v192, v198
	v_sub_f32_e32 v200, v197, v198
	v_exp_f32_e32 v199, v199
	v_exp_f32_e32 v200, v200
	v_mov_b32_e32 v192, v198
	v_fma_f32 v193, v193, v199, v200
	v_mul_f32_e32 v168, v168, v199
	v_mul_f32_e32 v169, v169, v199
	v_mul_f32_e32 v170, v170, v199
	v_mul_f32_e32 v171, v171, v199
	v_mul_f32_e32 v172, v172, v199
	v_mul_f32_e32 v173, v173, v199
	v_mul_f32_e32 v174, v174, v199
	v_mul_f32_e32 v175, v175, v199
	v_fmac_f32_e32 v168, v200, v56
	v_fmac_f32_e32 v169, v200, v57
	v_fmac_f32_e32 v170, v200, v58
	v_fmac_f32_e32 v171, v200, v59
	v_fmac_f32_e32 v172, v200, v60
	v_fmac_f32_e32 v173, v200, v61
	v_fmac_f32_e32 v174, v200, v62
	v_fmac_f32_e32 v175, v200, v63
	v_add_f32_e32 v194, v194, v196
	s_waitcnt vmcnt(12)
; __device__ __forceinline__ float fexp2(float x) { return __builtin_amdgcn_exp2f(x); }
; __device__ __forceinline__ void attn_sample_item(const P& p, int wi, int lane) {
;     ...
;         for (int jj = 0; jj < 33; ++jj) {
;             const int j = 4 * jj + kg; const bool valid = j <= 128; const int jc = valid ? j : 128;
;             const int idx = 2048 + i - d * jc;
;             f32x4 k0, k1, v0, v1;
;             if (idx < 2048) { const size_t off = (((size_t)bs * 2048 + idx) * 8 + h) * 128 + 8 * li;
;                 k0 = __builtin_nontemporal_load((const f32x4*)(p.cache_k + off)); k1 = __builtin_nontemporal_load((const f32x4*)(p.cache_k + off + 4)); v0 = __builtin_nontemporal_load((const f32x4*)(p.cache_v + off)); v1 = __builtin_nontemporal_load((const f32x4*)(p.cache_v + off + 4)); }
;             else { const int nr = bs * 4 + (idx - 2048); const float rsn = rstd1[TP + nr]; const int c0 = 4096 + h * 128 + 8 * li;
;                 k0 = acc1_4(ACC1, nr, c0) * rsn; k1 = acc1_4(ACC1, nr, c0 + 4) * rsn; v0 = acc1_4(ACC1, nr, c0 + 1024) * rsn; v1 = acc1_4(ACC1, nr, c0 + 1028) * rsn; }
;             float dot = (q[0] * k0[0] + q[1] * k0[1]) + (q[2] * k0[2] + q[3] * k0[3]) + (q[4] * k1[0] + q[5] * k1[1]) + (q[6] * k1[2] + q[7] * k1[3]);
;             dot += __shfl_xor(dot, 1); dot += __shfl_xor(dot, 2); dot += __shfl_xor(dot, 4); dot += __shfl_xor(dot, 8);
;             const float s = valid ? dot - sl * (float)(d * j) : -INFINITY;
;             const float mn = fmaxf(m, s), sc = fexp2(m - mn), pe = fexp2(s - mn);
;             l = l * sc + pe;
;             acc[0] = acc[0] * sc + pe * v0[0]; acc[1] = acc[1] * sc + pe * v0[1]; acc[2] = acc[2] * sc + pe * v0[2]; acc[3] = acc[3] * sc + pe * v0[3];
;             acc[4] = acc[4] * sc + pe * v1[0]; acc[5] = acc[5] * sc + pe * v1[1]; acc[6] = acc[6] * sc + pe * v1[2]; acc[7] = acc[7] * sc + pe * v1[3];
;             m = mn;
;         }
	v_fma_f32 v197, v160, v64, v194
	v_fmac_f32_e32 v197, v161, v65
	v_fmac_f32_e32 v197, v162, v66
	v_fmac_f32_e32 v197, v163, v67
	v_fmac_f32_e32 v197, v164, v68
	v_fmac_f32_e32 v197, v165, v69
	v_fmac_f32_e32 v197, v166, v70
	v_fmac_f32_e32 v197, v167, v71
	s_nop 1
	v_add_f32_dpp v197, v197, v197 row_ror:8 row_mask:0xf bank_mask:0xf
	s_nop 1
	v_add_f32_dpp v197, v197, v197 row_ror:4 row_mask:0xf bank_mask:0xf
	s_nop 1
	v_add_f32_dpp v197, v197, v197 row_ror:2 row_mask:0xf bank_mask:0xf
	s_nop 1
	v_add_f32_dpp v197, v197, v197 row_ror:1 row_mask:0xf bank_mask:0xf
	v_max_f32_e32 v198, v192, v197
	v_sub_f32_e32 v199, v192, v198
	v_sub_f32_e32 v200, v197, v198
	v_exp_f32_e32 v199, v199
	v_exp_f32_e32 v200, v200
	v_mov_b32_e32 v192, v198
	v_fma_f32 v193, v193, v199, v200
	v_mul_f32_e32 v168, v168, v199
	v_mul_f32_e32 v169, v169, v199
	v_mul_f32_e32 v170, v170, v199
	v_mul_f32_e32 v171, v171, v199
	v_mul_f32_e32 v172, v172, v199
	v_mul_f32_e32 v173, v173, v199
	v_mul_f32_e32 v174, v174, v199
	v_mul_f32_e32 v175, v175, v199
	v_fmac_f32_e32 v168, v200, v72
	v_fmac_f32_e32 v169, v200, v73
	v_fmac_f32_e32 v170, v200, v74
	v_fmac_f32_e32 v171, v200, v75
	v_fmac_f32_e32 v172, v200, v76
	v_fmac_f32_e32 v173, v200, v77
	v_fmac_f32_e32 v174, v200, v78
	v_fmac_f32_e32 v175, v200, v79
	v_add_f32_e32 v194, v194, v196
	s_waitcnt vmcnt(8)
	v_fma_f32 v197, v160, v80, v194
	v_fmac_f32_e32 v197, v161, v81
	v_fmac_f32_e32 v197, v162, v82
	v_fmac_f32_e32 v197, v163, v83
	v_fmac_f32_e32 v197, v164, v84
	v_fmac_f32_e32 v197, v165, v85
	v_fmac_f32_e32 v197, v166, v86
	v_fmac_f32_e32 v197, v167, v87
	s_nop 1
	v_add_f32_dpp v197, v197, v197 row_ror:8 row_mask:0xf bank_mask:0xf
	s_nop 1
	v_add_f32_dpp v197, v197, v197 row_ror:4 row_mask:0xf bank_mask:0xf
	s_nop 1
	v_add_f32_dpp v197, v197, v197 row_ror:2 row_mask:0xf bank_mask:0xf
	s_nop 1
	v_add_f32_dpp v197, v197, v197 row_ror:1 row_mask:0xf bank_mask:0xf
	v_max_f32_e32 v198, v192, v197
	v_sub_f32_e32 v199, v192, v198
	v_sub_f32_e32 v200, v197, v198
	v_exp_f32_e32 v199, v199
	v_exp_f32_e32 v200, v200
	v_mov_b32_e32 v192, v198
	v_fma_f32 v193, v193, v199, v200
	v_mul_f32_e32 v168, v168, v199
	v_mul_f32_e32 v169, v169, v199
	v_mul_f32_e32 v170, v170, v199
	v_mul_f32_e32 v171, v171, v199
	v_mul_f32_e32 v172, v172, v199
	v_mul_f32_e32 v173, v173, v199
	v_mul_f32_e32 v174, v174, v199
	v_mul_f32_e32 v175, v175, v199
	v_fmac_f32_e32 v168, v200, v88
	v_fmac_f32_e32 v169, v200, v89
	v_fmac_f32_e32 v170, v200, v90
	v_fmac_f32_e32 v171, v200, v91
	v_fmac_f32_e32 v172, v200, v92
	v_fmac_f32_e32 v173, v200, v93
	v_fmac_f32_e32 v174, v200, v94
	v_fmac_f32_e32 v175, v200, v95
	v_add_f32_e32 v194, v194, v196
	s_waitcnt vmcnt(4)
	v_fma_f32 v197, v160, v96, v194
	v_fmac_f32_e32 v197, v161, v97
	v_fmac_f32_e32 v197, v162, v98
	v_fmac_f32_e32 v197, v163, v99
	v_fmac_f32_e32 v197, v164, v100
	v_fmac_f32_e32 v197, v165, v101
	v_fmac_f32_e32 v197, v166, v102
	v_fmac_f32_e32 v197, v167, v103
	s_nop 1
	v_add_f32_dpp v197, v197, v197 row_ror:8 row_mask:0xf bank_mask:0xf
	s_nop 1
	v_add_f32_dpp v197, v197, v197 row_ror:4 row_mask:0xf bank_mask:0xf
	s_nop 1
	v_add_f32_dpp v197, v197, v197 row_ror:2 row_mask:0xf bank_mask:0xf
	s_nop 1
	v_add_f32_dpp v197, v197, v197 row_ror:1 row_mask:0xf bank_mask:0xf
	v_max_f32_e32 v198, v192, v197
	v_sub_f32_e32 v199, v192, v198
	v_sub_f32_e32 v200, v197, v198
	v_exp_f32_e32 v199, v199
	v_exp_f32_e32 v200, v200
	v_mov_b32_e32 v192, v198
	v_fma_f32 v193, v193, v199, v200
	v_mul_f32_e32 v168, v168, v199
	v_mul_f32_e32 v169, v169, v199
	v_mul_f32_e32 v170, v170, v199
	v_mul_f32_e32 v171, v171, v199
	v_mul_f32_e32 v172, v172, v199
	v_mul_f32_e32 v173, v173, v199
	v_mul_f32_e32 v174, v174, v199
	v_mul_f32_e32 v175, v175, v199
	v_fmac_f32_e32 v168, v200, v104
	v_fmac_f32_e32 v169, v200, v105
	v_fmac_f32_e32 v170, v200, v106
	v_fmac_f32_e32 v171, v200, v107
	v_fmac_f32_e32 v172, v200, v108
	v_fmac_f32_e32 v173, v200, v109
	v_fmac_f32_e32 v174, v200, v110
	v_fmac_f32_e32 v175, v200, v111
	v_add_f32_e32 v194, v194, v196
	s_waitcnt vmcnt(0)
; __device__ __forceinline__ float fexp2(float x) { return __builtin_amdgcn_exp2f(x); }
; __device__ __forceinline__ void attn_sample_item(const P& p, int wi, int lane) {
;     ...
;             float dot = (q[0] * k0[0] + q[1] * k0[1]) + (q[2] * k0[2] + q[3] * k0[3]) + (q[4] * k1[0] + q[5] * k1[1]) + (q[6] * k1[2] + q[7] * k1[3]);
;             dot += __shfl_xor(dot, 1); dot += __shfl_xor(dot, 2); dot += __shfl_xor(dot, 4); dot += __shfl_xor(dot, 8);
;             const float s = valid ? dot - sl * (float)(d * j) : -INFINITY;
;             const float mn = fmaxf(m, s), sc = fexp2(m - mn), pe = fexp2(s - mn);
;             l = l * sc + pe;
;             acc[0] = acc[0] * sc + pe * v0[0]; acc[1] = acc[1] * sc + pe * v0[1]; acc[2] = acc[2] * sc + pe * v0[2]; acc[3] = acc[3] * sc + pe * v0[3];
;             acc[4] = acc[4] * sc + pe * v1[0]; acc[5] = acc[5] * sc + pe * v1[1]; acc[6] = acc[6] * sc + pe * v1[2]; acc[7] = acc[7] * sc + pe * v1[3];
;             m = mn;
;         }
;     }
;     float mt = fmaxf(m, __shfl_xor(m, 16)); mt = fmaxf(mt, __shfl_xor(mt, 32));
;     const float f = fexp2(m - mt);
;     l *= f; l += __shfl_xor(l, 16); l += __shfl_xor(l, 32);
;     const float inv = 1.f / l;
;     float* o = (float*)(ws + O_ATTS) + (size_t)srow * 1024 + h * 128 + 8 * li;
; #pragma unroll
;     for (int e = 0; e < 8; ++e) { float a = acc[e] * f; a += __shfl_xor(a, 16); a += __shfl_xor(a, 32); acc[e] = a * inv; }
;     if (kg == 0) { *(f32x4*)o = (f32x4){acc[0], acc[1], acc[2], acc[3]}; *(f32x4*)(o + 4) = (f32x4){acc[4], acc[5], acc[6], acc[7]}; }
	v_fma_f32 v197, v160, v112, v194
	v_fmac_f32_e32 v197, v161, v113
	v_fmac_f32_e32 v197, v162, v114
	v_fmac_f32_e32 v197, v163, v115
	v_fmac_f32_e32 v197, v164, v116
	v_fmac_f32_e32 v197, v165, v117
	v_fmac_f32_e32 v197, v166, v118
	v_fmac_f32_e32 v197, v167, v119
	s_nop 1
	v_add_f32_dpp v197, v197, v197 row_ror:8 row_mask:0xf bank_mask:0xf
	s_nop 1
	v_add_f32_dpp v197, v197, v197 row_ror:4 row_mask:0xf bank_mask:0xf
	s_nop 1
	v_add_f32_dpp v197, v197, v197 row_ror:2 row_mask:0xf bank_mask:0xf
	s_nop 1
	v_add_f32_dpp v197, v197, v197 row_ror:1 row_mask:0xf bank_mask:0xf
	v_max_f32_e32 v198, v192, v197
	v_sub_f32_e32 v199, v192, v198
	v_sub_f32_e32 v200, v197, v198
	v_exp_f32_e32 v199, v199
	v_exp_f32_e32 v200, v200
	v_mov_b32_e32 v192, v198
	v_fma_f32 v193, v193, v199, v200
	v_mul_f32_e32 v168, v168, v199
	v_mul_f32_e32 v169, v169, v199
	v_mul_f32_e32 v170, v170, v199
	v_mul_f32_e32 v171, v171, v199
	v_mul_f32_e32 v172, v172, v199
	v_mul_f32_e32 v173, v173, v199
	v_mul_f32_e32 v174, v174, v199
	v_mul_f32_e32 v175, v175, v199
	v_fmac_f32_e32 v168, v200, v120
	v_fmac_f32_e32 v169, v200, v121
	v_fmac_f32_e32 v170, v200, v122
	v_fmac_f32_e32 v171, v200, v123
	v_fmac_f32_e32 v172, v200, v124
	v_fmac_f32_e32 v173, v200, v125
	v_fmac_f32_e32 v174, v200, v126
	v_fmac_f32_e32 v175, v200, v127
	v_and_b32_e32 v182, 63, v230
	v_xor_b32_e32 v183, 16, v182
	v_lshlrev_b32_e32 v183, 2, v183
	v_xor_b32_e32 v182, 32, v182
	v_lshlrev_b32_e32 v182, 2, v182
	ds_bpermute_b32 v197, v183, v192
	s_waitcnt lgkmcnt(0)
	v_max_f32_e32 v198, v192, v197
	ds_bpermute_b32 v197, v182, v198
	s_waitcnt lgkmcnt(0)
	v_max_f32_e32 v198, v198, v197
	v_sub_f32_e32 v199, v192, v198
	v_exp_f32_e32 v199, v199
	s_nop 0
	v_mul_f32_e32 v193, v193, v199
	v_mul_f32_e32 v168, v168, v199
	v_mul_f32_e32 v169, v169, v199
	v_mul_f32_e32 v170, v170, v199
	v_mul_f32_e32 v171, v171, v199
	v_mul_f32_e32 v172, v172, v199
	v_mul_f32_e32 v173, v173, v199
	v_mul_f32_e32 v174, v174, v199
	v_mul_f32_e32 v175, v175, v199
	ds_bpermute_b32 v0, v183, v193
	ds_bpermute_b32 v1, v183, v168
	ds_bpermute_b32 v2, v183, v169
	ds_bpermute_b32 v3, v183, v170
	ds_bpermute_b32 v4, v183, v171
	ds_bpermute_b32 v5, v183, v172
	ds_bpermute_b32 v6, v183, v173
	ds_bpermute_b32 v7, v183, v174
	ds_bpermute_b32 v8, v183, v175
	s_waitcnt lgkmcnt(0)
	v_add_f32_e32 v193, v193, v0
	v_add_f32_e32 v168, v168, v1
	v_add_f32_e32 v169, v169, v2
	v_add_f32_e32 v170, v170, v3
	v_add_f32_e32 v171, v171, v4
	v_add_f32_e32 v172, v172, v5
	v_add_f32_e32 v173, v173, v6
	v_add_f32_e32 v174, v174, v7
	v_add_f32_e32 v175, v175, v8
	ds_bpermute_b32 v0, v182, v193
	ds_bpermute_b32 v1, v182, v168
	ds_bpermute_b32 v2, v182, v169
	ds_bpermute_b32 v3, v182, v170
	ds_bpermute_b32 v4, v182, v171
	ds_bpermute_b32 v5, v182, v172
	ds_bpermute_b32 v6, v182, v173
	ds_bpermute_b32 v7, v182, v174
	ds_bpermute_b32 v8, v182, v175
	s_waitcnt lgkmcnt(0)
	v_add_f32_e32 v193, v193, v0
	v_add_f32_e32 v168, v168, v1
	v_add_f32_e32 v169, v169, v2
	v_add_f32_e32 v170, v170, v3
	v_add_f32_e32 v171, v171, v4
	v_add_f32_e32 v172, v172, v5
	v_add_f32_e32 v173, v173, v6
	v_add_f32_e32 v174, v174, v7
	v_add_f32_e32 v175, v175, v8
	v_rcp_f32_e32 v197, v193
	s_nop 0
	v_fma_f32 v198, -v193, v197, 1.0
	v_fma_f32 v197, v198, v197, v197
	v_mul_f32_e32 v168, v168, v197
	v_mul_f32_e32 v169, v169, v197
	v_mul_f32_e32 v170, v170, v197
	v_mul_f32_e32 v171, v171, v197
	v_mul_f32_e32 v172, v172, v197
	v_mul_f32_e32 v173, v173, v197
	v_mul_f32_e32 v174, v174, v197
	v_mul_f32_e32 v175, v175, v197
	v_and_b32_e32 v182, 15, v230
	v_lshlrev_b32_e32 v182, 4, v182
	s_lshl_b32 s43, s17, 12
	s_add_u32 s43, s43, s23
	v_add_u32_e32 v182, s43, v182
	s_mov_b64 exec, 0xffff
	global_store_dwordx4 v182, v[168:171], s[30:31]
	global_store_dwordx4 v182, v[172:175], s[30:31] offset:256
	s_mov_b64 exec, -1
	s_add_i32 s3, s3, s77
	s_cmpk_gt_i32 s3, 0x3ff
	s_cbranch_scc0 .Las_item
